# XCD-local barrier: the last arriver (its own atomic returns count = target) leaves without a poll; no sleep between polls
# speedup vs baseline: 1.0009x; 1.0003x over previous
; __device__ __forceinline__ unsigned xb_ld(unsigned* p)              { return __hip_atomic_load(p, __ATOMIC_RELAXED, __HIP_MEMORY_SCOPE_AGENT); }
; __device__ __forceinline__ unsigned xb_add(unsigned* p, unsigned v) { return __hip_atomic_fetch_add(p, v, __ATOMIC_RELAXED, __HIP_MEMORY_SCOPE_AGENT); }
; #define XB_SPIN(cond, bar) do { unsigned _sp = 0; while (cond) { __builtin_amdgcn_s_sleep(1); \
;     if ((++_sp & 255u) == 0u) { if (xb_ld(&(bar)[XB_TMO])) break; if (_sp > XB_SPIN_CAP) { atomicAdd(&(bar)[XB_TMO], 1u); break; } } } } while (0)
; __device__ __forceinline__ void xcd_barrier(const XcdBarrier& b) {
;     ...
;         const unsigned old = xb_add(&bar[XB_XSUB(bx)], 1u);
;         const unsigned gen = old / nloc;
;         if (old + 1u == (gen + 1u) * nloc) {
;             __builtin_amdgcn_fence(__ATOMIC_RELEASE, "agent");
;             asm volatile("s_waitcnt vmcnt(0)" ::: "memory");
;             const unsigned og = xb_add(&bar[XB_TOP], 1u);
;             const unsigned tg = og / nx;
;             if (og + 1u == (tg + 1u) * nx) xb_add(&bar[XB_TOPGEN], 1u);
;             else XB_SPIN(xb_ld(&bar[XB_TOPGEN]) == tg, bar);
;             __builtin_amdgcn_fence(__ATOMIC_ACQUIRE, "agent");
;             xb_add(&bar[XB_XGEN(bx)], 1u);
;             asm volatile("s_waitcnt vmcnt(0)" ::: "memory");
;         } else {
;             XB_SPIN(xb_ld(&bar[XB_XGEN(bx)]) == gen, bar);
.Lwc_pskip_2:
	s_cmp_eq_u32 s99, 0
	s_cbranch_scc1 .Lxb_full_1
	v_readlane_b32 s2, v254, 2
	v_mov_b32_e32 v1, 1
	s_lshl_b32 s2, s2, 8
	s_mov_b32 s98, 0
	v_mov_b32_e32 v0, s2
	buffer_inv sc1
	global_atomic_add v1, v0, v1, s[82:83] offset:1152 sc0
	s_waitcnt vmcnt(0)
	v_add_u32_e32 v2, 1, v1
	v_lshrrev_b32_e32 v1, 5, v1
	v_add_u32_e32 v1, 1, v1
	v_lshlrev_b32_e32 v1, 5, v1
	v_cmp_lt_u32_e32 vcc, v2, v1
	s_cbranch_vccz .Lxb_done_1

; __device__ __forceinline__ unsigned xb_ld(unsigned* p)              { return __hip_atomic_load(p, __ATOMIC_RELAXED, __HIP_MEMORY_SCOPE_AGENT); }
; __device__ __forceinline__ unsigned xb_add(unsigned* p, unsigned v) { return __hip_atomic_fetch_add(p, v, __ATOMIC_RELAXED, __HIP_MEMORY_SCOPE_AGENT); }
; #define XB_SPIN(cond, bar) do { unsigned _sp = 0; while (cond) { __builtin_amdgcn_s_sleep(1); \
;     if ((++_sp & 255u) == 0u) { if (xb_ld(&(bar)[XB_TMO])) break; if (_sp > XB_SPIN_CAP) { atomicAdd(&(bar)[XB_TMO], 1u); break; } } } } while (0)
; __device__ __forceinline__ void xcd_barrier(const XcdBarrier& b) {
;     ...
;         const unsigned old = xb_add(&bar[XB_XSUB(bx)], 1u);
;         const unsigned gen = old / nloc;
;         if (old + 1u == (gen + 1u) * nloc) {
;             __builtin_amdgcn_fence(__ATOMIC_RELEASE, "agent");
;             asm volatile("s_waitcnt vmcnt(0)" ::: "memory");
;             const unsigned og = xb_add(&bar[XB_TOP], 1u);
;             const unsigned tg = og / nx;
;             if (og + 1u == (tg + 1u) * nx) xb_add(&bar[XB_TOPGEN], 1u);
;             else XB_SPIN(xb_ld(&bar[XB_TOPGEN]) == tg, bar);
;             __builtin_amdgcn_fence(__ATOMIC_ACQUIRE, "agent");
;             xb_add(&bar[XB_XGEN(bx)], 1u);
;             asm volatile("s_waitcnt vmcnt(0)" ::: "memory");
;         } else {
;             XB_SPIN(xb_ld(&bar[XB_XGEN(bx)]) == gen, bar);
.Lwc_iskip_a4:
	s_and_saveexec_b64 s[0:1], s[66:67]
	s_cbranch_execz .LBB0_101
	v_mov_b32_e32 v61, 0
	global_load_dword v60, v61, s[82:83] offset:256 sc1
	s_cmp_eq_u32 s99, 0
	s_cbranch_scc1 .Lxb_full_3
	v_readlane_b32 s2, v254, 2
	v_mov_b32_e32 v1, 1
	s_lshl_b32 s2, s2, 8
	s_mov_b32 s98, 0
	v_mov_b32_e32 v0, s2
	buffer_inv sc1
	global_atomic_add v1, v0, v1, s[82:83] offset:1152 sc0
	s_waitcnt vmcnt(0)
	v_add_u32_e32 v2, 1, v1
	v_lshrrev_b32_e32 v1, 5, v1
	v_add_u32_e32 v1, 1, v1
	v_lshlrev_b32_e32 v1, 5, v1
	v_cmp_lt_u32_e32 vcc, v2, v1
	s_cbranch_vccz .Lxb_done_3
